# code placement: the five K-loop heads aligned to 64 bytes, on top of the K-loop + fixup variant
# baseline (speedup 1.0000x reference)
; #define LAS __attribute__((address_space(3)))
; #define PG8_STAGE(bufoff, gbase, voff) do { _Pragma("unroll") for (int _i = 0; _i < 2; ++_i) \
;         __builtin_amdgcn_global_load_lds((const unsigned*)((const char*)(gbase) + (voff)[_i]), (LAS unsigned*)(lds + (bufoff) + ldsw + _i * 8192), 16, 0, 0); } while (0)
; #define PG8_WAIT_V(n) asm volatile("s_waitcnt vmcnt(" #n ")" ::: "memory")
; #define PG8_BAR __builtin_amdgcn_s_barrier()
; __device__ __forceinline__ void lnfold_prefetch(LAS float* vl, const float* stats, const float* gW, const float* bW, const Unit& u, int wr, int wc, int lane) {
;     LAS float* slot = vl + (wr * 4 + wc) * 512;
;     const int rowb = u.pm * BM + wr * 64 + (lane >> 5) * HALF + (lane & 31) * 2;
;     const int col = u.pn * BM + wc * 32 + (lane < 32 ? lane : 96 + lane);
;     __builtin_amdgcn_global_load_lds((const unsigned*)(stats + 2 * (size_t)rowb), (LAS unsigned*)slot, 16, 0, 0);
;     __builtin_amdgcn_global_load_lds((const unsigned*)(gW + col), (LAS unsigned*)(slot + 256), 4, 0, 0);
;     __builtin_amdgcn_global_load_lds((const unsigned*)(bW + col), (LAS unsigned*)(slot + 320), 4, 0, 0);
; template <class Epi>
; __device__ __forceinline__ void gemm_phase(LAS unsigned char* lds, const Gemm g0, const StaticOrder& S, const Epi& E) {
;     ...
;     f32x4 acc[2][2][4][2];
; #pragma unroll
;     for (int a = 0; a < 2; ++a)
; #pragma unroll
;         for (int b = 0; b < 2; ++b)
; #pragma unroll
;             for (int m = 0; m < 4; ++m)
; #pragma unroll
;                 for (int n = 0; n < 2; ++n) acc[a][b][m][n] = (f32x4){0.f, 0.f, 0.f, 0.f};
;     f16x8 At[4][2], B0[2][2], B1[2][2];
;     const char* cA = (const char*)g.A + (size_t)cur.pm * tstep; const char* cB = (const char*)g.Bt + (size_t)cur.pn * tstep;
;     PG8_STAGE(PG8_SB(0, 0), cB, voffB); PG8_STAGE(PG8_SA(0, 0), cA, voffA); PG8_STAGE(PG8_SB(0, 1), cB + hstep, voffB); PG8_STAGE(PG8_SA(0, 1), cA + hstep, voffA);
;     if (wr == 1) PG8_BAR;
;     PG8_WAIT_V(4); PG8_BAR;
;     PG8_STAGE(PG8_SB(1, 0), cB + kstep, voffB); PG8_STAGE(PG8_SA(1, 0), cA + kstep, voffA); PG8_STAGE(PG8_SB(1, 1), cB + hstep + kstep, voffB);
;     PG8_WAIT_V(6); PG8_BAR;
;     for (;;) {
;         const bool has_next = S.next(ui + 1, nxt);
;         const char* nA = has_next ? (const char*)g.A + (size_t)nxt.pm * tstep : cA; const char* nB = has_next ? (const char*)g.Bt + (size_t)nxt.pn * tstep : cB;
.LBB0_197:
	s_ashr_i32 s37, s36, 31
	v_mov_b64_e32 v[2:3], 0x300
	s_lshl_b64 s[24:25], s[36:37], 20
	v_cmp_lt_i64_e32 vcc, s[38:39], v[2:3]
	s_add_u32 s38, s8, s24
	s_addc_u32 s39, s9, s25
	s_and_b64 s[24:25], vcc, exec
	s_cselect_b32 s75, s39, s51
	s_cselect_b32 s80, s38, s50
	s_ashr_i32 s35, s34, 31
	s_lshl_b64 s[24:25], s[34:35], 20
	s_add_u32 s48, s10, s24
	s_addc_u32 s49, s11, s25
	s_and_b64 s[24:25], vcc, exec
	s_cselect_b32 s81, s49, s1
	s_cselect_b32 s82, s48, s0
	s_lshl_b32 s37, s22, 8
	s_lshl_b32 s35, s74, 8
	v_add_u32_e32 v2, s37, v215
	v_add_u32_e32 v4, s35, v216
	s_add_u32 s24, s0, 0x100
	v_ashrrev_i32_e32 v3, 31, v2
	v_ashrrev_i32_e32 v5, 31, v4
	s_addc_u32 s25, s1, 0
	v_lshlrev_b64 v[4:5], 2, v[4:5]
	v_lshl_add_u64 v[134:135], v[2:3], 3, s[14:15]
	s_add_u32 s0, s50, 0x80080
	v_mov_b32_e32 v2, 0
	v_lshl_add_u64 v[130:131], s[26:27], 0, v[4:5]
	v_lshl_add_u64 v[132:133], s[20:21], 0, v[4:5]
	s_addc_u32 s1, s51, 0
	s_mov_b32 s83, -2
	v_mov_b32_e32 v3, v2
	v_mov_b32_e32 v4, v2
	v_mov_b32_e32 v5, v2
	v_mov_b32_e32 v6, v2
	v_mov_b32_e32 v7, v2
	v_mov_b32_e32 v8, v2
	v_mov_b32_e32 v9, v2
	v_mov_b32_e32 v10, v2
	v_mov_b32_e32 v11, v2
	v_mov_b32_e32 v12, v2
	v_mov_b32_e32 v13, v2
	v_mov_b32_e32 v14, v2
	v_mov_b32_e32 v15, v2
	v_mov_b32_e32 v16, v2
	v_mov_b32_e32 v17, v2
	v_mov_b32_e32 v26, v2
	v_mov_b32_e32 v27, v2
	v_mov_b32_e32 v28, v2
	v_mov_b32_e32 v29, v2
	v_mov_b32_e32 v34, v2
	v_mov_b32_e32 v35, v2
	v_mov_b32_e32 v36, v2
	v_mov_b32_e32 v37, v2
	v_mov_b32_e32 v42, v2
	v_mov_b32_e32 v43, v2
	v_mov_b32_e32 v44, v2
	v_mov_b32_e32 v45, v2
	v_mov_b32_e32 v46, v2
	v_mov_b32_e32 v47, v2
	v_mov_b32_e32 v48, v2
	v_mov_b32_e32 v49, v2
	v_mov_b32_e32 v18, v2
	v_mov_b32_e32 v19, v2
	v_mov_b32_e32 v20, v2
	v_mov_b32_e32 v21, v2
	v_mov_b32_e32 v22, v2
	v_mov_b32_e32 v23, v2
	v_mov_b32_e32 v24, v2
	v_mov_b32_e32 v25, v2
	v_mov_b32_e32 v30, v2
	v_mov_b32_e32 v31, v2
	v_mov_b32_e32 v32, v2
	v_mov_b32_e32 v33, v2
	v_mov_b32_e32 v38, v2
	v_mov_b32_e32 v39, v2
	v_mov_b32_e32 v40, v2
	v_mov_b32_e32 v41, v2
	v_mov_b32_e32 v50, v2
	v_mov_b32_e32 v51, v2
	v_mov_b32_e32 v52, v2
	v_mov_b32_e32 v53, v2
	v_mov_b32_e32 v54, v2
	v_mov_b32_e32 v55, v2
	v_mov_b32_e32 v56, v2
	v_mov_b32_e32 v57, v2
	v_mov_b32_e32 v58, v2
	v_mov_b32_e32 v59, v2
	v_mov_b32_e32 v60, v2
	v_mov_b32_e32 v61, v2
	v_mov_b32_e32 v62, v2
	v_mov_b32_e32 v63, v2
	v_mov_b32_e32 v64, v2
	v_mov_b32_e32 v65, v2
	v_mov_b32_e32 v66, v2
	v_mov_b32_e32 v67, v2
	v_mov_b32_e32 v68, v2
	v_mov_b32_e32 v69, v2
	v_mov_b32_e32 v70, v2
	v_mov_b32_e32 v71, v2
	v_mov_b32_e32 v72, v2
	v_mov_b32_e32 v73, v2
	v_mov_b32_e32 v74, v2
	v_mov_b32_e32 v75, v2
	v_mov_b32_e32 v76, v2
	v_mov_b32_e32 v77, v2
	v_mov_b32_e32 v78, v2
	v_mov_b32_e32 v79, v2
	v_mov_b32_e32 v80, v2
	v_mov_b32_e32 v81, v2
	v_mov_b32_e32 v90, v2
	v_mov_b32_e32 v91, v2
	v_mov_b32_e32 v92, v2
	v_mov_b32_e32 v93, v2
	v_mov_b32_e32 v94, v2
	v_mov_b32_e32 v95, v2
	v_mov_b32_e32 v96, v2
	v_mov_b32_e32 v97, v2
	v_mov_b32_e32 v106, v2
	v_mov_b32_e32 v107, v2
	v_mov_b32_e32 v108, v2
	v_mov_b32_e32 v109, v2
	v_mov_b32_e32 v114, v2
	v_mov_b32_e32 v115, v2
	v_mov_b32_e32 v116, v2
	v_mov_b32_e32 v117, v2
	v_mov_b32_e32 v82, v2
	v_mov_b32_e32 v83, v2
	v_mov_b32_e32 v84, v2
	v_mov_b32_e32 v85, v2
	v_mov_b32_e32 v86, v2
	v_mov_b32_e32 v87, v2
	v_mov_b32_e32 v88, v2
	v_mov_b32_e32 v89, v2
	v_mov_b32_e32 v98, v2
	v_mov_b32_e32 v99, v2
	v_mov_b32_e32 v100, v2
	v_mov_b32_e32 v101, v2
	v_mov_b32_e32 v102, v2
	v_mov_b32_e32 v103, v2
	v_mov_b32_e32 v104, v2
	v_mov_b32_e32 v105, v2
	v_mov_b32_e32 v110, v2
	v_mov_b32_e32 v111, v2
	v_mov_b32_e32 v112, v2
	v_mov_b32_e32 v113, v2
	v_mov_b32_e32 v118, v2
	v_mov_b32_e32 v119, v2
	v_mov_b32_e32 v120, v2
	v_mov_b32_e32 v121, v2
	v_mov_b32_e32 v122, v2
	v_mov_b32_e32 v123, v2
	v_mov_b32_e32 v124, v2
	v_mov_b32_e32 v125, v2
	v_mov_b32_e32 v126, v2
	v_mov_b32_e32 v127, v2
	v_mov_b32_e32 v128, v2
	v_mov_b32_e32 v129, v2
	v_add_u32_e32 v160, 0x80, v178
	v_add_u32_e32 v162, 0x80, v174
	v_add_u32_e32 v164, 0x80, v180
	v_add_u32_e32 v170, 0x80, v176
	v_add_u32_e32 v161, 0x10000, v214
	s_branch .LBB0_199
	.p2align	6

; #define PG8_STAGE(bufoff, gbase, voff) do { _Pragma("unroll") for (int _i = 0; _i < 2; ++_i) \
;         __builtin_amdgcn_global_load_lds((const unsigned*)((const char*)(gbase) + (voff)[_i]), (LAS unsigned*)(lds + (bufoff) + ldsw + _i * 8192), 16, 0, 0); } while (0)
; #define PG8_WAIT_V(n) asm volatile("s_waitcnt vmcnt(" #n ")" ::: "memory")
; #define PG8_BAR __builtin_amdgcn_s_barrier()
; template <class Epi>
; __device__ __forceinline__ void gemm_phase(LAS unsigned char* lds, const Gemm g0, const StaticOrder& S, const Epi& E) {
;     ...
;     f32x4 acc[2][2][4][2];
; #pragma unroll
;     for (int a = 0; a < 2; ++a)
; #pragma unroll
;         for (int b = 0; b < 2; ++b)
; #pragma unroll
;             for (int m = 0; m < 4; ++m)
; #pragma unroll
;                 for (int n = 0; n < 2; ++n) acc[a][b][m][n] = (f32x4){0.f, 0.f, 0.f, 0.f};
;     f16x8 At[4][2], B0[2][2], B1[2][2];
;     const char* cA = (const char*)g.A + (size_t)cur.pm * tstep; const char* cB = (const char*)g.Bt + (size_t)cur.pn * tstep;
;     PG8_STAGE(PG8_SB(0, 0), cB, voffB); PG8_STAGE(PG8_SA(0, 0), cA, voffA); PG8_STAGE(PG8_SB(0, 1), cB + hstep, voffB); PG8_STAGE(PG8_SA(0, 1), cA + hstep, voffA);
;     if (wr == 1) PG8_BAR;
;     PG8_WAIT_V(4); PG8_BAR;
;     PG8_STAGE(PG8_SB(1, 0), cB + kstep, voffB); PG8_STAGE(PG8_SA(1, 0), cA + kstep, voffA); PG8_STAGE(PG8_SB(1, 1), cB + hstep + kstep, voffB);
;     PG8_WAIT_V(6); PG8_BAR;
;     for (;;) {
;         const bool has_next = S.next(ui + 1, nxt);
;         const char* nA = has_next ? (const char*)g.A + (size_t)nxt.pm * tstep : cA; const char* nB = has_next ? (const char*)g.Bt + (size_t)nxt.pn * tstep : cB;
.LBB0_301:
	s_ashr_i32 s15, s14, 31
	v_cmp_lt_i64_e32 vcc, s[20:21], v[248:249]
	s_lshl_b64 s[20:21], s[14:15], 20
	s_add_u32 s20, s8, s20
	s_addc_u32 s21, s9, s21
	s_and_b64 s[22:23], vcc, exec
	s_cselect_b32 s15, s21, s35
	s_cselect_b32 s52, s20, s34
	s_ashr_i32 s13, s12, 31
	s_lshl_b64 s[22:23], s[12:13], 20
	s_add_u32 s26, s10, s22
	s_addc_u32 s27, s11, s23
	s_and_b64 s[22:23], vcc, exec
	s_cselect_b32 s13, s27, s7
	s_cselect_b32 s24, s26, s6
	s_add_u32 s25, s6, 0x100
	s_addc_u32 s53, s7, 0
	s_add_u32 s6, s34, 0x80080
	v_mov_b32_e32 v2, 0
	s_addc_u32 s7, s35, 0
	s_mov_b32 s58, -2
	v_mov_b32_e32 v3, v2
	v_mov_b32_e32 v4, v2
	v_mov_b32_e32 v5, v2
	v_mov_b32_e32 v6, v2
	v_mov_b32_e32 v7, v2
	v_mov_b32_e32 v8, v2
	v_mov_b32_e32 v9, v2
	v_mov_b32_e32 v18, v2
	v_mov_b32_e32 v19, v2
	v_mov_b32_e32 v20, v2
	v_mov_b32_e32 v21, v2
	v_mov_b32_e32 v22, v2
	v_mov_b32_e32 v23, v2
	v_mov_b32_e32 v24, v2
	v_mov_b32_e32 v25, v2
	v_mov_b32_e32 v34, v2
	v_mov_b32_e32 v35, v2
	v_mov_b32_e32 v36, v2
	v_mov_b32_e32 v37, v2
	v_mov_b32_e32 v38, v2
	v_mov_b32_e32 v39, v2
	v_mov_b32_e32 v40, v2
	v_mov_b32_e32 v41, v2
	v_mov_b32_e32 v50, v2
	v_mov_b32_e32 v51, v2
	v_mov_b32_e32 v52, v2
	v_mov_b32_e32 v53, v2
	v_mov_b32_e32 v54, v2
	v_mov_b32_e32 v55, v2
	v_mov_b32_e32 v56, v2
	v_mov_b32_e32 v57, v2
	v_mov_b32_e32 v10, v2
	v_mov_b32_e32 v11, v2
	v_mov_b32_e32 v12, v2
	v_mov_b32_e32 v13, v2
	v_mov_b32_e32 v14, v2
	v_mov_b32_e32 v15, v2
	v_mov_b32_e32 v16, v2
	v_mov_b32_e32 v17, v2
	v_mov_b32_e32 v26, v2
	v_mov_b32_e32 v27, v2
	v_mov_b32_e32 v28, v2
	v_mov_b32_e32 v29, v2
	v_mov_b32_e32 v30, v2
	v_mov_b32_e32 v31, v2
	v_mov_b32_e32 v32, v2
	v_mov_b32_e32 v33, v2
	v_mov_b32_e32 v42, v2
	v_mov_b32_e32 v43, v2
	v_mov_b32_e32 v44, v2
	v_mov_b32_e32 v45, v2
	v_mov_b32_e32 v46, v2
	v_mov_b32_e32 v47, v2
	v_mov_b32_e32 v48, v2
	v_mov_b32_e32 v49, v2
	v_mov_b32_e32 v58, v2
	v_mov_b32_e32 v59, v2
	v_mov_b32_e32 v60, v2
	v_mov_b32_e32 v61, v2
	v_mov_b32_e32 v62, v2
	v_mov_b32_e32 v63, v2
	v_mov_b32_e32 v64, v2
	v_mov_b32_e32 v65, v2
	v_mov_b32_e32 v66, v2
	v_mov_b32_e32 v67, v2
	v_mov_b32_e32 v68, v2
	v_mov_b32_e32 v69, v2
	v_mov_b32_e32 v70, v2
	v_mov_b32_e32 v71, v2
	v_mov_b32_e32 v72, v2
	v_mov_b32_e32 v73, v2
	v_mov_b32_e32 v82, v2
	v_mov_b32_e32 v83, v2
	v_mov_b32_e32 v84, v2
	v_mov_b32_e32 v85, v2
	v_mov_b32_e32 v86, v2
	v_mov_b32_e32 v87, v2
	v_mov_b32_e32 v88, v2
	v_mov_b32_e32 v89, v2
	v_mov_b32_e32 v98, v2
	v_mov_b32_e32 v99, v2
	v_mov_b32_e32 v100, v2
	v_mov_b32_e32 v101, v2
	v_mov_b32_e32 v102, v2
	v_mov_b32_e32 v103, v2
	v_mov_b32_e32 v104, v2
	v_mov_b32_e32 v105, v2
	v_mov_b32_e32 v114, v2
	v_mov_b32_e32 v115, v2
	v_mov_b32_e32 v116, v2
	v_mov_b32_e32 v117, v2
	v_mov_b32_e32 v118, v2
	v_mov_b32_e32 v119, v2
	v_mov_b32_e32 v120, v2
	v_mov_b32_e32 v121, v2
	v_mov_b32_e32 v74, v2
	v_mov_b32_e32 v75, v2
	v_mov_b32_e32 v76, v2
	v_mov_b32_e32 v77, v2
	v_mov_b32_e32 v78, v2
	v_mov_b32_e32 v79, v2
	v_mov_b32_e32 v80, v2
	v_mov_b32_e32 v81, v2
	v_mov_b32_e32 v90, v2
	v_mov_b32_e32 v91, v2
	v_mov_b32_e32 v92, v2
	v_mov_b32_e32 v93, v2
	v_mov_b32_e32 v94, v2
	v_mov_b32_e32 v95, v2
	v_mov_b32_e32 v96, v2
	v_mov_b32_e32 v97, v2
	v_mov_b32_e32 v106, v2
	v_mov_b32_e32 v107, v2
	v_mov_b32_e32 v108, v2
	v_mov_b32_e32 v109, v2
	v_mov_b32_e32 v110, v2
	v_mov_b32_e32 v111, v2
	v_mov_b32_e32 v112, v2
	v_mov_b32_e32 v113, v2
	v_mov_b32_e32 v122, v2
	v_mov_b32_e32 v123, v2
	v_mov_b32_e32 v124, v2
	v_mov_b32_e32 v125, v2
	v_mov_b32_e32 v126, v2
	v_mov_b32_e32 v127, v2
	v_mov_b32_e32 v128, v2
	v_mov_b32_e32 v129, v2
	v_add_u32_e32 v146, 0x80, v134
	v_add_u32_e32 v160, 0x80, v130
	v_add_u32_e32 v162, 0x80, v136
	v_add_u32_e32 v164, 0x80, v132
	v_add_u32_e32 v161, 0x10000, v148
	.p2align	6

; #define PG8_STAGE(bufoff, gbase, voff) do { _Pragma("unroll") for (int _i = 0; _i < 2; ++_i) \
;         __builtin_amdgcn_global_load_lds((const unsigned*)((const char*)(gbase) + (voff)[_i]), (LAS unsigned*)(lds + (bufoff) + ldsw + _i * 8192), 16, 0, 0); } while (0)
; #define PG8_WAIT_V(n) asm volatile("s_waitcnt vmcnt(" #n ")" ::: "memory")
; #define PG8_BAR __builtin_amdgcn_s_barrier()
; template <class Epi>
; __device__ __forceinline__ void gemm_phase(LAS unsigned char* lds, const Gemm g0, const StaticOrder& S, const Epi& E) {
;     ...
;     f32x4 acc[2][2][4][2];
; #pragma unroll
;     for (int a = 0; a < 2; ++a)
; #pragma unroll
;         for (int b = 0; b < 2; ++b)
; #pragma unroll
;             for (int m = 0; m < 4; ++m)
; #pragma unroll
;                 for (int n = 0; n < 2; ++n) acc[a][b][m][n] = (f32x4){0.f, 0.f, 0.f, 0.f};
;     f16x8 At[4][2], B0[2][2], B1[2][2];
;     const char* cA = (const char*)g.A + (size_t)cur.pm * tstep; const char* cB = (const char*)g.Bt + (size_t)cur.pn * tstep;
;     PG8_STAGE(PG8_SB(0, 0), cB, voffB); PG8_STAGE(PG8_SA(0, 0), cA, voffA); PG8_STAGE(PG8_SB(0, 1), cB + hstep, voffB); PG8_STAGE(PG8_SA(0, 1), cA + hstep, voffA);
;     if (wr == 1) PG8_BAR;
;     PG8_WAIT_V(4); PG8_BAR;
;     PG8_STAGE(PG8_SB(1, 0), cB + kstep, voffB); PG8_STAGE(PG8_SA(1, 0), cA + kstep, voffA); PG8_STAGE(PG8_SB(1, 1), cB + hstep + kstep, voffB);
;     PG8_WAIT_V(6); PG8_BAR;
;     for (;;) {
;         const bool has_next = S.next(ui + 1, nxt);
;         const char* nA = has_next ? (const char*)g.A + (size_t)nxt.pm * tstep : cA; const char* nB = has_next ? (const char*)g.Bt + (size_t)nxt.pn * tstep : cB;
.LBB0_511:
	s_ashr_i32 s15, s14, 31
	s_lshl_b64 s[22:23], s[14:15], 20
	v_cmp_lt_i64_e32 vcc, s[36:37], v[168:169]
	s_add_u32 s36, s92, s22
	s_addc_u32 s37, s93, s23
	s_and_b64 s[22:23], vcc, exec
	s_cselect_b32 s15, s37, s49
	s_cselect_b32 s24, s36, s48
	s_ashr_i32 s53, s52, 31
	s_lshl_b64 s[22:23], s[52:53], 20
	s_add_u32 s38, s96, s22
	s_addc_u32 s39, s97, s23
	s_and_b64 s[22:23], vcc, exec
	s_cselect_b32 s25, s39, s13
	s_cselect_b32 s53, s38, s12
	s_add_u32 vcc_lo, s12, 0x100
	s_addc_u32 vcc_hi, s13, 0
	s_add_u32 s12, s48, 0x80080
	v_mov_b32_e32 v2, 0
	s_addc_u32 s13, s49, 0
	s_mov_b32 s22, -2
	v_mov_b32_e32 v3, v2
	v_mov_b32_e32 v4, v2
	v_mov_b32_e32 v5, v2
	v_mov_b32_e32 v6, v2
	v_mov_b32_e32 v7, v2
	v_mov_b32_e32 v8, v2
	v_mov_b32_e32 v9, v2
	v_mov_b32_e32 v18, v2
	v_mov_b32_e32 v19, v2
	v_mov_b32_e32 v20, v2
	v_mov_b32_e32 v21, v2
	v_mov_b32_e32 v22, v2
	v_mov_b32_e32 v23, v2
	v_mov_b32_e32 v24, v2
	v_mov_b32_e32 v25, v2
	v_mov_b32_e32 v34, v2
	v_mov_b32_e32 v35, v2
	v_mov_b32_e32 v36, v2
	v_mov_b32_e32 v37, v2
	v_mov_b32_e32 v38, v2
	v_mov_b32_e32 v39, v2
	v_mov_b32_e32 v40, v2
	v_mov_b32_e32 v41, v2
	v_mov_b32_e32 v50, v2
	v_mov_b32_e32 v51, v2
	v_mov_b32_e32 v52, v2
	v_mov_b32_e32 v53, v2
	v_mov_b32_e32 v54, v2
	v_mov_b32_e32 v55, v2
	v_mov_b32_e32 v56, v2
	v_mov_b32_e32 v57, v2
	v_mov_b32_e32 v10, v2
	v_mov_b32_e32 v11, v2
	v_mov_b32_e32 v12, v2
	v_mov_b32_e32 v13, v2
	v_mov_b32_e32 v14, v2
	v_mov_b32_e32 v15, v2
	v_mov_b32_e32 v16, v2
	v_mov_b32_e32 v17, v2
	v_mov_b32_e32 v26, v2
	v_mov_b32_e32 v27, v2
	v_mov_b32_e32 v28, v2
	v_mov_b32_e32 v29, v2
	v_mov_b32_e32 v30, v2
	v_mov_b32_e32 v31, v2
	v_mov_b32_e32 v32, v2
	v_mov_b32_e32 v33, v2
	v_mov_b32_e32 v42, v2
	v_mov_b32_e32 v43, v2
	v_mov_b32_e32 v44, v2
	v_mov_b32_e32 v45, v2
	v_mov_b32_e32 v46, v2
	v_mov_b32_e32 v47, v2
	v_mov_b32_e32 v48, v2
	v_mov_b32_e32 v49, v2
	v_mov_b32_e32 v58, v2
	v_mov_b32_e32 v59, v2
	v_mov_b32_e32 v60, v2
	v_mov_b32_e32 v61, v2
	v_mov_b32_e32 v62, v2
	v_mov_b32_e32 v63, v2
	v_mov_b32_e32 v64, v2
	v_mov_b32_e32 v65, v2
	v_mov_b32_e32 v66, v2
	v_mov_b32_e32 v67, v2
	v_mov_b32_e32 v68, v2
	v_mov_b32_e32 v69, v2
	v_mov_b32_e32 v70, v2
	v_mov_b32_e32 v71, v2
	v_mov_b32_e32 v72, v2
	v_mov_b32_e32 v73, v2
	v_mov_b32_e32 v82, v2
	v_mov_b32_e32 v83, v2
	v_mov_b32_e32 v84, v2
	v_mov_b32_e32 v85, v2
	v_mov_b32_e32 v86, v2
	v_mov_b32_e32 v87, v2
	v_mov_b32_e32 v88, v2
	v_mov_b32_e32 v89, v2
	v_mov_b32_e32 v98, v2
	v_mov_b32_e32 v99, v2
	s_waitcnt vmcnt(0)
	v_mov_b32_e32 v100, v2
	v_mov_b32_e32 v101, v2
	v_mov_b32_e32 v102, v2
	v_mov_b32_e32 v103, v2
	v_mov_b32_e32 v104, v2
	v_mov_b32_e32 v105, v2
	v_mov_b32_e32 v114, v2
	v_mov_b32_e32 v115, v2
	v_mov_b32_e32 v116, v2
	v_mov_b32_e32 v117, v2
	v_mov_b32_e32 v118, v2
	v_mov_b32_e32 v119, v2
	v_mov_b32_e32 v120, v2
	v_mov_b32_e32 v121, v2
	v_mov_b32_e32 v74, v2
	v_mov_b32_e32 v75, v2
	v_mov_b32_e32 v76, v2
	v_mov_b32_e32 v77, v2
	v_mov_b32_e32 v78, v2
	v_mov_b32_e32 v79, v2
	v_mov_b32_e32 v80, v2
	v_mov_b32_e32 v81, v2
	v_mov_b32_e32 v90, v2
	v_mov_b32_e32 v91, v2
	v_mov_b32_e32 v92, v2
	v_mov_b32_e32 v93, v2
	v_mov_b32_e32 v94, v2
	v_mov_b32_e32 v95, v2
	v_mov_b32_e32 v96, v2
	v_mov_b32_e32 v97, v2
	v_mov_b32_e32 v106, v2
	v_mov_b32_e32 v107, v2
	v_mov_b32_e32 v108, v2
	v_mov_b32_e32 v109, v2
	v_mov_b32_e32 v110, v2
	v_mov_b32_e32 v111, v2
	v_mov_b32_e32 v112, v2
	v_mov_b32_e32 v113, v2
	v_mov_b32_e32 v130, v2
	v_mov_b32_e32 v131, v2
	v_mov_b32_e32 v132, v2
	v_mov_b32_e32 v133, v2
	v_mov_b32_e32 v134, v2
	v_mov_b32_e32 v135, v2
	v_mov_b32_e32 v136, v2
	v_mov_b32_e32 v137, v2
	v_add_u32_e32 v164, 0x80, v174
	v_add_u32_e32 v165, 0x10000, v205
	.p2align	6

; #define LAS __attribute__((address_space(3)))
; #define PG8_STAGE(bufoff, gbase, voff) do { _Pragma("unroll") for (int _i = 0; _i < 2; ++_i) \
;         __builtin_amdgcn_global_load_lds((const unsigned*)((const char*)(gbase) + (voff)[_i]), (LAS unsigned*)(lds + (bufoff) + ldsw + _i * 8192), 16, 0, 0); } while (0)
; #define PG8_WAIT_V(n) asm volatile("s_waitcnt vmcnt(" #n ")" ::: "memory")
; #define PG8_BAR __builtin_amdgcn_s_barrier()
; __device__ __forceinline__ void lnfold_prefetch(LAS float* vl, const float* stats, const float* gW, const float* bW, const Unit& u, int wr, int wc, int lane) {
;     LAS float* slot = vl + (wr * 4 + wc) * 512;
;     const int rowb = u.pm * BM + wr * 64 + (lane >> 5) * HALF + (lane & 31) * 2;
;     const int col = u.pn * BM + wc * 32 + (lane < 32 ? lane : 96 + lane);
;     __builtin_amdgcn_global_load_lds((const unsigned*)(stats + 2 * (size_t)rowb), (LAS unsigned*)slot, 16, 0, 0);
;     __builtin_amdgcn_global_load_lds((const unsigned*)(gW + col), (LAS unsigned*)(slot + 256), 4, 0, 0);
;     __builtin_amdgcn_global_load_lds((const unsigned*)(bW + col), (LAS unsigned*)(slot + 320), 4, 0, 0);
; template <class Epi>
; __device__ __forceinline__ void gemm_phase(LAS unsigned char* lds, const Gemm g0, const StaticOrder& S, const Epi& E) {
;     ...
;     f32x4 acc[2][2][4][2];
; #pragma unroll
;     for (int a = 0; a < 2; ++a)
; #pragma unroll
;         for (int b = 0; b < 2; ++b)
; #pragma unroll
;             for (int m = 0; m < 4; ++m)
; #pragma unroll
;                 for (int n = 0; n < 2; ++n) acc[a][b][m][n] = (f32x4){0.f, 0.f, 0.f, 0.f};
;     f16x8 At[4][2], B0[2][2], B1[2][2];
;     const char* cA = (const char*)g.A + (size_t)cur.pm * tstep; const char* cB = (const char*)g.Bt + (size_t)cur.pn * tstep;
;     PG8_STAGE(PG8_SB(0, 0), cB, voffB); PG8_STAGE(PG8_SA(0, 0), cA, voffA); PG8_STAGE(PG8_SB(0, 1), cB + hstep, voffB); PG8_STAGE(PG8_SA(0, 1), cA + hstep, voffA);
;     if (wr == 1) PG8_BAR;
;     PG8_WAIT_V(4); PG8_BAR;
;     PG8_STAGE(PG8_SB(1, 0), cB + kstep, voffB); PG8_STAGE(PG8_SA(1, 0), cA + kstep, voffA); PG8_STAGE(PG8_SB(1, 1), cB + hstep + kstep, voffB);
;     PG8_WAIT_V(6); PG8_BAR;
;     for (;;) {
;         const bool has_next = S.next(ui + 1, nxt);
;         const char* nA = has_next ? (const char*)g.A + (size_t)nxt.pm * tstep : cA; const char* nB = has_next ? (const char*)g.Bt + (size_t)nxt.pn * tstep : cB;
.LBB0_619:
	s_ashr_i32 s37, s36, 31
	s_lshl_b64 s[24:25], s[36:37], 20
	v_cmp_lt_i64_e32 vcc, s[38:39], v[230:231]
	s_add_u32 s38, s8, s24
	s_addc_u32 s39, s9, s25
	s_and_b64 s[24:25], vcc, exec
	s_cselect_b32 s37, s39, s53
	s_cselect_b32 s74, s38, s52
	s_ashr_i32 s35, s34, 31
	s_lshl_b64 s[24:25], s[34:35], 20
	s_add_u32 s48, s10, s24
	s_addc_u32 s49, s11, s25
	s_and_b64 s[24:25], vcc, exec
	s_cselect_b32 s35, s49, s51
	s_cselect_b32 s75, s48, s50
	s_lshl_b32 s80, s22, 8
	v_add_u32_e32 v2, s80, v193
	v_lshl_add_u32 v4, s71, 8, v201
	s_add_u32 s24, s50, 0x100
	v_ashrrev_i32_e32 v3, 31, v2
	v_ashrrev_i32_e32 v5, 31, v4
	s_addc_u32 s25, s51, 0
	v_lshlrev_b64 v[4:5], 2, v[4:5]
	v_lshl_add_u64 v[58:59], v[2:3], 3, s[14:15]
	s_add_u32 s50, s52, 0x80080
	v_mov_b32_e32 v2, 0
	v_lshl_add_u64 v[54:55], s[26:27], 0, v[4:5]
	v_lshl_add_u64 v[56:57], s[20:21], 0, v[4:5]
	s_addc_u32 s51, s53, 0
	s_mov_b32 s81, -2
	v_mov_b32_e32 v3, v2
	v_mov_b32_e32 v4, v2
	v_mov_b32_e32 v5, v2
	v_mov_b32_e32 v10, v2
	v_mov_b32_e32 v11, v2
	v_mov_b32_e32 v12, v2
	v_mov_b32_e32 v13, v2
	v_mov_b32_e32 v18, v2
	v_mov_b32_e32 v19, v2
	v_mov_b32_e32 v20, v2
	v_mov_b32_e32 v21, v2
	v_mov_b32_e32 v26, v2
	v_mov_b32_e32 v27, v2
	v_mov_b32_e32 v28, v2
	v_mov_b32_e32 v29, v2
	v_mov_b32_e32 v34, v2
	v_mov_b32_e32 v35, v2
	v_mov_b32_e32 v36, v2
	v_mov_b32_e32 v37, v2
	v_mov_b32_e32 v42, v2
	v_mov_b32_e32 v43, v2
	v_mov_b32_e32 v44, v2
	v_mov_b32_e32 v45, v2
	v_mov_b32_e32 v50, v2
	v_mov_b32_e32 v51, v2
	v_mov_b32_e32 v52, v2
	v_mov_b32_e32 v53, v2
	v_mov_b32_e32 v74, v2
	v_mov_b32_e32 v75, v2
	v_mov_b32_e32 v76, v2
	v_mov_b32_e32 v77, v2
	v_mov_b32_e32 v6, v2
	v_mov_b32_e32 v7, v2
	v_mov_b32_e32 v8, v2
	v_mov_b32_e32 v9, v2
	v_mov_b32_e32 v14, v2
	v_mov_b32_e32 v15, v2
	v_mov_b32_e32 v16, v2
	v_mov_b32_e32 v17, v2
	v_mov_b32_e32 v22, v2
	v_mov_b32_e32 v23, v2
	v_mov_b32_e32 v24, v2
	v_mov_b32_e32 v25, v2
	v_mov_b32_e32 v30, v2
	v_mov_b32_e32 v31, v2
	v_mov_b32_e32 v32, v2
	v_mov_b32_e32 v33, v2
	v_mov_b32_e32 v38, v2
	v_mov_b32_e32 v39, v2
	v_mov_b32_e32 v40, v2
	v_mov_b32_e32 v41, v2
	v_mov_b32_e32 v46, v2
	v_mov_b32_e32 v47, v2
	v_mov_b32_e32 v48, v2
	v_mov_b32_e32 v49, v2
	v_mov_b32_e32 v70, v2
	v_mov_b32_e32 v71, v2
	v_mov_b32_e32 v72, v2
	v_mov_b32_e32 v73, v2
	v_mov_b32_e32 v94, v2
	v_mov_b32_e32 v95, v2
	v_mov_b32_e32 v96, v2
	v_mov_b32_e32 v97, v2
	v_mov_b32_e32 v98, v2
	v_mov_b32_e32 v99, v2
	v_mov_b32_e32 v100, v2
	v_mov_b32_e32 v101, v2
	v_mov_b32_e32 v106, v2
	v_mov_b32_e32 v107, v2
	v_mov_b32_e32 v108, v2
	v_mov_b32_e32 v109, v2
	v_mov_b32_e32 v114, v2
	v_mov_b32_e32 v115, v2
	v_mov_b32_e32 v116, v2
	v_mov_b32_e32 v117, v2
	v_mov_b32_e32 v122, v2
	v_mov_b32_e32 v123, v2
	v_mov_b32_e32 v124, v2
	v_mov_b32_e32 v125, v2
	v_mov_b32_e32 v130, v2
	v_mov_b32_e32 v131, v2
	v_mov_b32_e32 v132, v2
	v_mov_b32_e32 v133, v2
	v_mov_b32_e32 v138, v2
	v_mov_b32_e32 v139, v2
	v_mov_b32_e32 v140, v2
	v_mov_b32_e32 v141, v2
	v_mov_b32_e32 v146, v2
	v_mov_b32_e32 v147, v2
	v_mov_b32_e32 v148, v2
	v_mov_b32_e32 v149, v2
	v_mov_b32_e32 v154, v2
	v_mov_b32_e32 v155, v2
	v_mov_b32_e32 v156, v2
	v_mov_b32_e32 v157, v2
	v_mov_b32_e32 v102, v2
	v_mov_b32_e32 v103, v2
	v_mov_b32_e32 v104, v2
	v_mov_b32_e32 v105, v2
	v_mov_b32_e32 v110, v2
	v_mov_b32_e32 v111, v2
	v_mov_b32_e32 v112, v2
	v_mov_b32_e32 v113, v2
	v_mov_b32_e32 v118, v2
	v_mov_b32_e32 v119, v2
	v_mov_b32_e32 v120, v2
	v_mov_b32_e32 v121, v2
	v_mov_b32_e32 v126, v2
	v_mov_b32_e32 v127, v2
	v_mov_b32_e32 v128, v2
	v_mov_b32_e32 v129, v2
	v_mov_b32_e32 v134, v2
	v_mov_b32_e32 v135, v2
	v_mov_b32_e32 v136, v2
	v_mov_b32_e32 v137, v2
	v_mov_b32_e32 v142, v2
	v_mov_b32_e32 v143, v2
	v_mov_b32_e32 v144, v2
	v_mov_b32_e32 v145, v2
	v_mov_b32_e32 v150, v2
	v_mov_b32_e32 v151, v2
	v_mov_b32_e32 v152, v2
	v_mov_b32_e32 v153, v2
	v_mov_b32_e32 v158, v2
	v_mov_b32_e32 v159, v2
	v_mov_b32_e32 v160, v2
	v_mov_b32_e32 v161, v2
	v_add_u32_e32 v186, 0x80, v178
	v_add_u32_e32 v190, 0x80, v174
	v_add_u32_e32 v198, 0x80, v180
	v_add_u32_e32 v202, 0x80, v176
	v_add_u32_e32 v187, 0x10000, v189
	s_branch .LBB0_621
	.p2align	6

; #define PG8_STAGE(bufoff, gbase, voff) do { _Pragma("unroll") for (int _i = 0; _i < 2; ++_i) \
;         __builtin_amdgcn_global_load_lds((const unsigned*)((const char*)(gbase) + (voff)[_i]), (LAS unsigned*)(lds + (bufoff) + ldsw + _i * 8192), 16, 0, 0); } while (0)
; #define PG8_WAIT_V(n) asm volatile("s_waitcnt vmcnt(" #n ")" ::: "memory")
; #define PG8_BAR __builtin_amdgcn_s_barrier()
; template <class Epi>
; __device__ __forceinline__ void gemm_phase(LAS unsigned char* lds, const Gemm g0, const StaticOrder& S, const Epi& E) {
;     ...
;     f32x4 acc[2][2][4][2];
; #pragma unroll
;     for (int a = 0; a < 2; ++a)
; #pragma unroll
;         for (int b = 0; b < 2; ++b)
; #pragma unroll
;             for (int m = 0; m < 4; ++m)
; #pragma unroll
;                 for (int n = 0; n < 2; ++n) acc[a][b][m][n] = (f32x4){0.f, 0.f, 0.f, 0.f};
;     f16x8 At[4][2], B0[2][2], B1[2][2];
;     const char* cA = (const char*)g.A + (size_t)cur.pm * tstep; const char* cB = (const char*)g.Bt + (size_t)cur.pn * tstep;
;     PG8_STAGE(PG8_SB(0, 0), cB, voffB); PG8_STAGE(PG8_SA(0, 0), cA, voffA); PG8_STAGE(PG8_SB(0, 1), cB + hstep, voffB); PG8_STAGE(PG8_SA(0, 1), cA + hstep, voffA);
;     if (wr == 1) PG8_BAR;
;     PG8_WAIT_V(4); PG8_BAR;
;     PG8_STAGE(PG8_SB(1, 0), cB + kstep, voffB); PG8_STAGE(PG8_SA(1, 0), cA + kstep, voffA); PG8_STAGE(PG8_SB(1, 1), cB + hstep + kstep, voffB);
;     PG8_WAIT_V(6); PG8_BAR;
;     for (;;) {
;         const bool has_next = S.next(ui + 1, nxt);
;         const char* nA = has_next ? (const char*)g.A + (size_t)nxt.pm * tstep : cA; const char* nB = has_next ? (const char*)g.Bt + (size_t)nxt.pn * tstep : cB;
.LBB0_671:
	s_add_u32 s24, s62, 0x100
	v_mov_b32_e32 v2, 0
	s_addc_u32 s25, s63, 0
	s_mov_b32 s22, -2
	s_waitcnt lgkmcnt(0)
	v_mov_b32_e32 v3, v2
	v_mov_b32_e32 v4, v2
	v_mov_b32_e32 v5, v2
	v_mov_b32_e32 v6, v2
	v_mov_b32_e32 v7, v2
	v_mov_b32_e32 v8, v2
	v_mov_b32_e32 v9, v2
	v_mov_b32_e32 v18, v2
	v_mov_b32_e32 v19, v2
	v_mov_b32_e32 v20, v2
	v_mov_b32_e32 v21, v2
	v_mov_b32_e32 v22, v2
	v_mov_b32_e32 v23, v2
	v_mov_b32_e32 v24, v2
	v_mov_b32_e32 v25, v2
	v_mov_b32_e32 v34, v2
	v_mov_b32_e32 v35, v2
	v_mov_b32_e32 v36, v2
	v_mov_b32_e32 v37, v2
	v_mov_b32_e32 v38, v2
	v_mov_b32_e32 v39, v2
	v_mov_b32_e32 v40, v2
	v_mov_b32_e32 v41, v2
	v_mov_b32_e32 v50, v2
	v_mov_b32_e32 v51, v2
	v_mov_b32_e32 v52, v2
	v_mov_b32_e32 v53, v2
	v_mov_b32_e32 v54, v2
	v_mov_b32_e32 v55, v2
	v_mov_b32_e32 v56, v2
	v_mov_b32_e32 v57, v2
	v_mov_b32_e32 v10, v2
	v_mov_b32_e32 v11, v2
	v_mov_b32_e32 v12, v2
	v_mov_b32_e32 v13, v2
	v_mov_b32_e32 v14, v2
	v_mov_b32_e32 v15, v2
	v_mov_b32_e32 v16, v2
	v_mov_b32_e32 v17, v2
	v_mov_b32_e32 v26, v2
	v_mov_b32_e32 v27, v2
	v_mov_b32_e32 v28, v2
	v_mov_b32_e32 v29, v2
	v_mov_b32_e32 v30, v2
	v_mov_b32_e32 v31, v2
	v_mov_b32_e32 v32, v2
	v_mov_b32_e32 v33, v2
	v_mov_b32_e32 v42, v2
	v_mov_b32_e32 v43, v2
	v_mov_b32_e32 v44, v2
	v_mov_b32_e32 v45, v2
	v_mov_b32_e32 v46, v2
	v_mov_b32_e32 v47, v2
	v_mov_b32_e32 v48, v2
	v_mov_b32_e32 v49, v2
	v_mov_b32_e32 v58, v2
	v_mov_b32_e32 v59, v2
	v_mov_b32_e32 v60, v2
	v_mov_b32_e32 v61, v2
	v_mov_b32_e32 v62, v2
	v_mov_b32_e32 v63, v2
	v_mov_b32_e32 v64, v2
	v_mov_b32_e32 v65, v2
	v_mov_b32_e32 v66, v2
	v_mov_b32_e32 v67, v2
	v_mov_b32_e32 v68, v2
	v_mov_b32_e32 v69, v2
	v_mov_b32_e32 v70, v2
	v_mov_b32_e32 v71, v2
	v_mov_b32_e32 v72, v2
	v_mov_b32_e32 v73, v2
	v_mov_b32_e32 v82, v2
	v_mov_b32_e32 v83, v2
	v_mov_b32_e32 v84, v2
	v_mov_b32_e32 v85, v2
	v_mov_b32_e32 v86, v2
	v_mov_b32_e32 v87, v2
	v_mov_b32_e32 v88, v2
	v_mov_b32_e32 v89, v2
	v_mov_b32_e32 v98, v2
	v_mov_b32_e32 v99, v2
	v_mov_b32_e32 v100, v2
	v_mov_b32_e32 v101, v2
	v_mov_b32_e32 v102, v2
	v_mov_b32_e32 v103, v2
	v_mov_b32_e32 v104, v2
	v_mov_b32_e32 v105, v2
	v_mov_b32_e32 v114, v2
	v_mov_b32_e32 v115, v2
	v_mov_b32_e32 v116, v2
	v_mov_b32_e32 v117, v2
	v_mov_b32_e32 v118, v2
	v_mov_b32_e32 v119, v2
	v_mov_b32_e32 v120, v2
	v_mov_b32_e32 v121, v2
	v_mov_b32_e32 v74, v2
	v_mov_b32_e32 v75, v2
	v_mov_b32_e32 v76, v2
	v_mov_b32_e32 v77, v2
	v_mov_b32_e32 v78, v2
	v_mov_b32_e32 v79, v2
	v_mov_b32_e32 v80, v2
	v_mov_b32_e32 v81, v2
	v_mov_b32_e32 v90, v2
	v_mov_b32_e32 v91, v2
	v_mov_b32_e32 v92, v2
	v_mov_b32_e32 v93, v2
	v_mov_b32_e32 v94, v2
	v_mov_b32_e32 v95, v2
	v_mov_b32_e32 v96, v2
	v_mov_b32_e32 v97, v2
	v_mov_b32_e32 v106, v2
	v_mov_b32_e32 v107, v2
	v_mov_b32_e32 v108, v2
	v_mov_b32_e32 v109, v2
	v_mov_b32_e32 v110, v2
	v_mov_b32_e32 v111, v2
	v_mov_b32_e32 v112, v2
	v_mov_b32_e32 v113, v2
	v_mov_b32_e32 v122, v2
	v_mov_b32_e32 v123, v2
	v_mov_b32_e32 v124, v2
	v_mov_b32_e32 v125, v2
	v_mov_b32_e32 v126, v2
	v_mov_b32_e32 v127, v2
	v_mov_b32_e32 v128, v2
	v_mov_b32_e32 v129, v2
	v_add_u32_e32 v200, 0x80, v174
	v_add_u32_e32 v218, 0x80, v158
	v_add_u32_e32 v226, 0x80, v176
	v_add_u32_e32 v228, 0x80, v160
	v_add_u32_e32 v201, 0x10000, v203
	.p2align	6
